# second measure: nt hint on the once-read phase-0 loads (f32 weights, x) on top of the best version
# speedup vs baseline: 1.0116x; 1.0086x over previous
; __device__ __forceinline__ void transpose_item(const float* W, int K, int N, bf16* WT, int mode, LAS float* scr, int item, int lane) {
;     const int nblk = N / 32, kb = item / nblk, nb = item % nblk, k0 = 64 * kb, n0 = 32 * nb;
;     int r0 = n0;
;     if (mode == 1) r0 = 256 * (n0 >> 7) + (n0 & 127);
;     else if (mode == 2) r0 = 256 * (n0 >> 7) + 128 + (n0 & 127);
; #pragma unroll 8
;     for (int i = 0; i < 32; ++i) { const int kk = 2 * i + (lane >> 5); scr[kk * 33 + (lane & 31)] = W[(size_t)(k0 + kk) * N + n0 + (lane & 31)]; }
;     asm volatile("s_waitcnt lgkmcnt(0)" ::: "memory");
.LBB0_23:
	s_lshl_b32 s45, s29, 1
	s_lshl_b32 s46, s43, 1
	v_or_b32_e32 v22, s46, v4
	s_add_i32 s47, s45, 4
	s_add_i32 s48, s46, 4
	s_add_i32 s49, s45, 8
	s_add_i32 s50, s46, 8
	s_add_i32 s51, s45, 12
	s_add_i32 s54, s46, 12
	s_add_i32 s55, s45, 16
	s_add_i32 s56, s46, 16
	s_add_i32 s57, s45, 20
	s_add_i32 s58, s46, 20
	s_add_i32 s59, s45, 24
	s_add_i32 s60, s46, 24
	s_add_i32 s61, s45, 28
	s_add_i32 s62, s46, 28
	v_or_b32_e32 v20, s45, v3
	v_ashrrev_i32_e32 v23, 31, v22
	v_or_b32_e32 v24, s47, v3
	v_or_b32_e32 v26, s48, v4
	v_or_b32_e32 v28, s49, v3
	v_or_b32_e32 v30, s50, v4
	v_or_b32_e32 v32, s51, v3
	v_or_b32_e32 v34, s54, v4
	v_or_b32_e32 v36, s55, v3
	v_or_b32_e32 v38, s56, v4
	v_or_b32_e32 v40, s57, v3
	v_or_b32_e32 v42, s58, v4
	v_or_b32_e32 v44, s59, v3
	v_or_b32_e32 v46, s60, v4
	v_or_b32_e32 v48, s61, v3
	v_or_b32_e32 v50, s62, v4
	v_ashrrev_i32_e32 v21, 31, v20
	v_lshlrev_b64 v[22:23], 12, v[22:23]
	v_ashrrev_i32_e32 v27, 31, v26
	v_ashrrev_i32_e32 v25, 31, v24
	v_ashrrev_i32_e32 v31, 31, v30
	v_ashrrev_i32_e32 v29, 31, v28
	v_ashrrev_i32_e32 v35, 31, v34
	v_ashrrev_i32_e32 v33, 31, v32
	v_ashrrev_i32_e32 v39, 31, v38
	v_ashrrev_i32_e32 v37, 31, v36
	v_ashrrev_i32_e32 v43, 31, v42
	v_ashrrev_i32_e32 v41, 31, v40
	v_ashrrev_i32_e32 v47, 31, v46
	v_ashrrev_i32_e32 v45, 31, v44
	v_ashrrev_i32_e32 v51, 31, v50
	v_ashrrev_i32_e32 v49, 31, v48
	v_lshlrev_b64 v[20:21], 12, v[20:21]
	v_lshl_add_u64 v[22:23], v[12:13], 0, v[22:23]
	v_lshlrev_b64 v[24:25], 12, v[24:25]
	v_lshlrev_b64 v[26:27], 12, v[26:27]
	v_lshlrev_b64 v[28:29], 12, v[28:29]
	v_lshlrev_b64 v[30:31], 12, v[30:31]
	v_lshlrev_b64 v[32:33], 12, v[32:33]
	v_lshlrev_b64 v[34:35], 12, v[34:35]
	v_lshlrev_b64 v[36:37], 12, v[36:37]
	v_lshlrev_b64 v[38:39], 12, v[38:39]
	v_lshlrev_b64 v[40:41], 12, v[40:41]
	v_lshlrev_b64 v[42:43], 12, v[42:43]
	v_lshlrev_b64 v[44:45], 12, v[44:45]
	v_lshlrev_b64 v[46:47], 12, v[46:47]
	v_lshlrev_b64 v[48:49], 12, v[48:49]
	v_lshlrev_b64 v[50:51], 12, v[50:51]
	v_lshl_add_u64 v[20:21], v[12:13], 0, v[20:21]
	v_lshl_add_u64 v[26:27], v[12:13], 0, v[26:27]
	v_lshl_add_u64 v[24:25], v[12:13], 0, v[24:25]
	v_lshl_add_u64 v[30:31], v[12:13], 0, v[30:31]
	v_lshl_add_u64 v[28:29], v[12:13], 0, v[28:29]
	v_lshl_add_u64 v[34:35], v[12:13], 0, v[34:35]
	v_lshl_add_u64 v[32:33], v[12:13], 0, v[32:33]
	v_lshl_add_u64 v[38:39], v[12:13], 0, v[38:39]
	v_lshl_add_u64 v[36:37], v[12:13], 0, v[36:37]
	v_lshl_add_u64 v[42:43], v[12:13], 0, v[42:43]
	v_lshl_add_u64 v[40:41], v[12:13], 0, v[40:41]
	v_lshl_add_u64 v[46:47], v[12:13], 0, v[46:47]
	v_lshl_add_u64 v[44:45], v[12:13], 0, v[44:45]
	v_lshl_add_u64 v[50:51], v[12:13], 0, v[50:51]
	v_lshl_add_u64 v[48:49], v[12:13], 0, v[48:49]
	global_load_dword v9, v[22:23], off nt
	global_load_dword v11, v[20:21], off nt
	global_load_dword v14, v[26:27], off nt
	global_load_dword v19, v[24:25], off nt
	global_load_dword v52, v[30:31], off nt
	global_load_dword v53, v[28:29], off nt
	global_load_dword v54, v[34:35], off nt
	global_load_dword v55, v[32:33], off nt
	global_load_dword v56, v[38:39], off nt
	global_load_dword v57, v[36:37], off nt
	global_load_dword v58, v[42:43], off nt
	global_load_dword v59, v[40:41], off nt
	global_load_dword v60, v[46:47], off nt
	global_load_dword v61, v[44:45], off nt
	global_load_dword v62, v[50:51], off nt
	global_load_dword v63, v[48:49], off nt
	v_or_b32_e32 v22, s45, v1
	v_or_b32_e32 v20, s46, v2
	s_add_i32 s43, s43, 16
	s_add_i32 s29, s29, 16
	s_add_i32 s44, s44, -16
	v_mad_u64_u32 v[20:21], s[52:53], v20, s35, v[6:7]
	v_mad_u64_u32 v[22:23], s[52:53], v22, s35, v[6:7]
	v_or_b32_e32 v21, s47, v1
	v_or_b32_e32 v23, s48, v2
	v_or_b32_e32 v30, s49, v1
	v_or_b32_e32 v28, s50, v2
	v_or_b32_e32 v34, s51, v1
	v_or_b32_e32 v32, s54, v2
	v_or_b32_e32 v38, s55, v1
	v_or_b32_e32 v36, s56, v2
	v_or_b32_e32 v42, s57, v1
	v_or_b32_e32 v40, s58, v2
	v_or_b32_e32 v46, s59, v1
	v_or_b32_e32 v44, s60, v2
	v_or_b32_e32 v50, s61, v1
	v_or_b32_e32 v48, s62, v2
	s_cmp_lg_u32 s44, 0
	v_mad_u64_u32 v[24:25], s[46:47], v23, s35, v[6:7]
	v_mad_u64_u32 v[26:27], s[46:47], v21, s35, v[6:7]
	v_mad_u64_u32 v[28:29], s[46:47], v28, s35, v[6:7]
	v_mad_u64_u32 v[30:31], s[46:47], v30, s35, v[6:7]
	v_mad_u64_u32 v[32:33], s[46:47], v32, s35, v[6:7]
	v_mad_u64_u32 v[34:35], s[46:47], v34, s35, v[6:7]
	v_mad_u64_u32 v[36:37], s[46:47], v36, s35, v[6:7]
	v_mad_u64_u32 v[38:39], s[46:47], v38, s35, v[6:7]
	v_mad_u64_u32 v[40:41], s[46:47], v40, s35, v[6:7]
	v_mad_u64_u32 v[42:43], s[46:47], v42, s35, v[6:7]
	v_mad_u64_u32 v[44:45], s[46:47], v44, s35, v[6:7]
	v_mad_u64_u32 v[46:47], s[46:47], v46, s35, v[6:7]
	v_mad_u64_u32 v[48:49], s[46:47], v48, s35, v[6:7]
	v_mad_u64_u32 v[50:51], s[46:47], v50, s35, v[6:7]
	s_waitcnt vmcnt(15)
	ds_write_b32 v20, v9
	s_waitcnt vmcnt(14)
	ds_write_b32 v22, v11
	s_waitcnt vmcnt(13)
	ds_write_b32 v24, v14
	s_waitcnt vmcnt(12)
	ds_write_b32 v26, v19
	s_waitcnt vmcnt(11)
	ds_write_b32 v28, v52
	s_waitcnt vmcnt(10)
	ds_write_b32 v30, v53
	s_waitcnt vmcnt(9)
	ds_write_b32 v32, v54
	s_waitcnt vmcnt(8)
	ds_write_b32 v34, v55
	s_waitcnt vmcnt(7)
	ds_write_b32 v36, v56
	s_waitcnt vmcnt(6)
	ds_write_b32 v38, v57
	s_waitcnt vmcnt(5)
	ds_write_b32 v40, v58
	s_waitcnt vmcnt(4)
	ds_write_b32 v42, v59
	s_waitcnt vmcnt(3)
	ds_write_b32 v44, v60
	s_waitcnt vmcnt(2)
	ds_write_b32 v46, v61
	s_waitcnt vmcnt(1)
	ds_write_b32 v48, v62
	s_waitcnt vmcnt(0)
	ds_write_b32 v50, v63
	s_cbranch_scc1 .LBB0_23
; #define LAS __attribute__((address_space(3)))
; __device__ __forceinline__ unsigned pk2(float lo, float hi) { return pg8::cvt_pk_bf16(lo, hi); }
; __device__ __forceinline__ void transpose_item(const float* W, int K, int N, bf16* WT, int mode, LAS float* scr, int item, int lane) {
;     ...
;     asm volatile("s_waitcnt lgkmcnt(0)" ::: "memory");
;     const int c = lane & 7;
; #pragma unroll
;     for (int j = 0; j < 4; ++j) { const int n = (lane >> 3) + 8 * j; const LAS float* s = scr + (8 * c) * 33 + n;
;         u32x4 o; o.x = pk2(s[0 * 33], s[1 * 33]); o.y = pk2(s[2 * 33], s[3 * 33]); o.z = pk2(s[4 * 33], s[5 * 33]); o.w = pk2(s[6 * 33], s[7 * 33]);
;         *(u32x4*)(WT + (size_t)(r0 + n) * K + k0 + 8 * c) = o; }
;     asm volatile("s_waitcnt lgkmcnt(0)" ::: "memory");
	s_waitcnt lgkmcnt(0)
	s_lshl_b64 s[44:45], s[2:3], 1
	ds_read2_b32 v[24:25], v15 offset0:33 offset1:41
	ds_read2_b32 v[26:27], v15 offset1:8
	ds_read2_b32 v[28:29], v15 offset0:66 offset1:74
	ds_read2_b32 v[30:31], v15 offset0:99 offset1:107
	ds_read2_b32 v[32:33], v15 offset0:132 offset1:140
	ds_read2_b32 v[34:35], v15 offset0:165 offset1:173
	ds_read2_b32 v[36:37], v15 offset0:198 offset1:206
	ds_read2_b32 v[38:39], v15 offset0:231 offset1:239
	s_add_u32 s44, s38, s44
	s_addc_u32 s45, s39, s45
	v_mov_b32_e32 v11, v5
	v_or_b32_e32 v3, s28, v7
	v_lshl_add_u64 v[12:13], s[44:45], 0, v[10:11]
	v_mul_u32_u24_e32 v3, 0xb00, v3
	v_lshl_add_u64 v[12:13], v[12:13], 0, s[18:19]
	v_lshlrev_b32_e32 v4, 1, v3
	s_waitcnt lgkmcnt(6)
	v_cvt_pk_bf16_f32 v20, v26, v24
	s_waitcnt lgkmcnt(4)
	v_cvt_pk_bf16_f32 v21, v28, v30
	s_waitcnt lgkmcnt(2)
	v_cvt_pk_bf16_f32 v22, v32, v34
	s_waitcnt lgkmcnt(0)
	v_cvt_pk_bf16_f32 v23, v36, v38
	v_lshl_add_u64 v[40:41], v[12:13], 0, v[4:5]
	global_store_dwordx4 v[40:41], v[20:23], off
	v_or_b32_e32 v3, s28, v16
	v_mul_u32_u24_e32 v3, 0xb00, v3
	v_cvt_pk_bf16_f32 v20, v27, v25
	v_cvt_pk_bf16_f32 v21, v29, v31
	v_cvt_pk_bf16_f32 v22, v33, v35
	v_cvt_pk_bf16_f32 v23, v37, v39
	ds_read2_b32 v[26:27], v15 offset0:16 offset1:24
	ds_read2_b32 v[28:29], v15 offset0:49 offset1:57
	ds_read2_b32 v[30:31], v15 offset0:82 offset1:90
	ds_read2_b32 v[32:33], v15 offset0:115 offset1:123
	ds_read2_b32 v[34:35], v15 offset0:148 offset1:156
	ds_read2_b32 v[36:37], v15 offset0:181 offset1:189
	ds_read2_b32 v[38:39], v15 offset0:214 offset1:222
	ds_read2_b32 v[40:41], v15 offset0:247 offset1:255
	v_lshlrev_b32_e32 v4, 1, v3
	v_or_b32_e32 v3, s28, v17
	v_mul_u32_u24_e32 v3, 0xb00, v3
	v_lshl_add_u64 v[24:25], v[12:13], 0, v[4:5]
	v_lshlrev_b32_e32 v4, 1, v3
	v_or_b32_e32 v3, s28, v18
	v_mul_u32_u24_e32 v3, 0xb00, v3
	global_store_dwordx4 v[24:25], v[20:23], off
	v_lshl_add_u64 v[24:25], v[12:13], 0, v[4:5]
	v_lshlrev_b32_e32 v4, 1, v3
	s_waitcnt lgkmcnt(6)
	v_cvt_pk_bf16_f32 v20, v26, v28
	s_waitcnt lgkmcnt(4)
	v_cvt_pk_bf16_f32 v21, v30, v32
	s_waitcnt lgkmcnt(2)
	v_cvt_pk_bf16_f32 v22, v34, v36
	s_waitcnt lgkmcnt(0)
	v_cvt_pk_bf16_f32 v23, v38, v40
	global_store_dwordx4 v[24:25], v[20:23], off
	v_lshl_add_u64 v[12:13], v[12:13], 0, v[4:5]
	s_mov_b64 s[28:29], 0
	v_cvt_pk_bf16_f32 v20, v27, v29
	v_cvt_pk_bf16_f32 v21, v31, v33
	v_cvt_pk_bf16_f32 v22, v35, v37
	v_cvt_pk_bf16_f32 v23, v39, v41
	global_store_dwordx4 v[12:13], v[20:23], off
	s_waitcnt lgkmcnt(0)

; #define LAS __attribute__((address_space(3)))
; __device__ __forceinline__ unsigned pk2(float lo, float hi) { return pg8::cvt_pk_bf16(lo, hi); }
; __device__ __forceinline__ void transpose_item(const float* W, int K, int N, bf16* WT, int mode, LAS float* scr, int item, int lane) {
;     const int nblk = N / 32, kb = item / nblk, nb = item % nblk, k0 = 64 * kb, n0 = 32 * nb;
;     int r0 = n0;
;     if (mode == 1) r0 = 256 * (n0 >> 7) + (n0 & 127);
;     else if (mode == 2) r0 = 256 * (n0 >> 7) + 128 + (n0 & 127);
; #pragma unroll 8
;     for (int i = 0; i < 32; ++i) { const int kk = 2 * i + (lane >> 5); scr[kk * 33 + (lane & 31)] = W[(size_t)(k0 + kk) * N + n0 + (lane & 31)]; }
;     asm volatile("s_waitcnt lgkmcnt(0)" ::: "memory");
;     const int c = lane & 7;
; #pragma unroll
;     for (int j = 0; j < 4; ++j) { const int n = (lane >> 3) + 8 * j; const LAS float* s = scr + (8 * c) * 33 + n;
;         u32x4 o; o.x = pk2(s[0 * 33], s[1 * 33]); o.y = pk2(s[2 * 33], s[3 * 33]); o.z = pk2(s[4 * 33], s[5 * 33]); o.w = pk2(s[6 * 33], s[7 * 33]);
;         *(u32x4*)(WT + (size_t)(r0 + n) * K + k0 + 8 * c) = o; }
.LBB0_27:
	s_lshl_b32 s48, s43, 1
	s_lshl_b32 s49, s44, 1
	v_or_b32_e32 v9, s48, v3
	v_or_b32_e32 v11, s49, v4
	s_add_i32 s50, s48, 4
	s_add_i32 s51, s49, 4
	s_add_i32 s52, s48, 8
	s_add_i32 s53, s49, 8
	s_add_i32 s54, s48, 12
	s_add_i32 s55, s49, 12
	s_add_i32 s56, s48, 16
	s_add_i32 s57, s49, 16
	s_add_i32 s58, s48, 20
	s_add_i32 s59, s49, 20
	s_add_i32 s60, s48, 24
	s_add_i32 s61, s49, 24
	s_add_i32 s62, s48, 28
	s_add_i32 s63, s49, 28
	v_mad_u64_u32 v[20:21], s[46:47], v11, s36, v[12:13]
	v_mad_u64_u32 v[22:23], s[46:47], v9, s36, v[12:13]
	v_or_b32_e32 v9, s50, v3
	v_or_b32_e32 v11, s51, v4
	v_or_b32_e32 v14, s52, v3
	v_or_b32_e32 v19, s53, v4
	v_or_b32_e32 v34, s54, v3
	v_or_b32_e32 v32, s55, v4
	v_or_b32_e32 v38, s56, v3
	v_or_b32_e32 v36, s57, v4
	v_or_b32_e32 v42, s58, v3
	v_or_b32_e32 v40, s59, v4
	v_or_b32_e32 v46, s60, v3
	v_or_b32_e32 v44, s61, v4
	v_or_b32_e32 v50, s62, v3
	v_or_b32_e32 v48, s63, v4
	v_mad_u64_u32 v[24:25], s[46:47], v11, s36, v[12:13]
	v_mad_u64_u32 v[26:27], s[46:47], v9, s36, v[12:13]
	v_mad_u64_u32 v[28:29], s[46:47], v19, s36, v[12:13]
	v_mad_u64_u32 v[30:31], s[46:47], v14, s36, v[12:13]
	v_mad_u64_u32 v[32:33], s[46:47], v32, s36, v[12:13]
	v_mad_u64_u32 v[34:35], s[46:47], v34, s36, v[12:13]
	v_mad_u64_u32 v[36:37], s[46:47], v36, s36, v[12:13]
	v_mad_u64_u32 v[38:39], s[46:47], v38, s36, v[12:13]
	v_mad_u64_u32 v[40:41], s[46:47], v40, s36, v[12:13]
	v_mad_u64_u32 v[42:43], s[46:47], v42, s36, v[12:13]
	v_mad_u64_u32 v[44:45], s[46:47], v44, s36, v[12:13]
	v_mad_u64_u32 v[46:47], s[46:47], v46, s36, v[12:13]
	v_mad_u64_u32 v[48:49], s[46:47], v48, s36, v[12:13]
	v_mad_u64_u32 v[50:51], s[46:47], v50, s36, v[12:13]
	global_load_dword v9, v[20:21], off nt
	global_load_dword v11, v[22:23], off nt
	global_load_dword v14, v[24:25], off nt
	global_load_dword v19, v[26:27], off nt
	global_load_dword v52, v[28:29], off nt
	global_load_dword v53, v[30:31], off nt
	global_load_dword v54, v[32:33], off nt
	global_load_dword v55, v[34:35], off nt
	global_load_dword v56, v[36:37], off nt
	global_load_dword v57, v[38:39], off nt
	global_load_dword v58, v[40:41], off nt
	global_load_dword v59, v[42:43], off nt
	global_load_dword v60, v[44:45], off nt
	global_load_dword v61, v[46:47], off nt
	global_load_dword v62, v[48:49], off nt
	global_load_dword v63, v[50:51], off nt
	v_or_b32_e32 v22, s48, v1
	v_or_b32_e32 v20, s49, v2
	s_add_i32 s44, s44, 16
	s_add_i32 s43, s43, 16
	s_add_i32 s45, s45, -16
	v_mad_u64_u32 v[20:21], s[46:47], v20, s35, v[6:7]
	v_mad_u64_u32 v[22:23], s[46:47], v22, s35, v[6:7]
	v_or_b32_e32 v21, s50, v1
	v_or_b32_e32 v23, s51, v2
	v_or_b32_e32 v30, s52, v1
	v_or_b32_e32 v28, s53, v2
	v_or_b32_e32 v34, s54, v1
	v_or_b32_e32 v32, s55, v2
	v_or_b32_e32 v38, s56, v1
	v_or_b32_e32 v36, s57, v2
	v_or_b32_e32 v42, s58, v1
	v_or_b32_e32 v40, s59, v2
	v_or_b32_e32 v46, s60, v1
	v_or_b32_e32 v44, s61, v2
	v_or_b32_e32 v50, s62, v1
	v_or_b32_e32 v48, s63, v2
	s_cmp_lg_u32 s45, 0
	v_mad_u64_u32 v[24:25], s[46:47], v23, s35, v[6:7]
	v_mad_u64_u32 v[26:27], s[46:47], v21, s35, v[6:7]
	v_mad_u64_u32 v[28:29], s[46:47], v28, s35, v[6:7]
	v_mad_u64_u32 v[30:31], s[46:47], v30, s35, v[6:7]
	v_mad_u64_u32 v[32:33], s[46:47], v32, s35, v[6:7]
	v_mad_u64_u32 v[34:35], s[46:47], v34, s35, v[6:7]
	v_mad_u64_u32 v[36:37], s[46:47], v36, s35, v[6:7]
	v_mad_u64_u32 v[38:39], s[46:47], v38, s35, v[6:7]
	v_mad_u64_u32 v[40:41], s[46:47], v40, s35, v[6:7]
	v_mad_u64_u32 v[42:43], s[46:47], v42, s35, v[6:7]
	v_mad_u64_u32 v[44:45], s[46:47], v44, s35, v[6:7]
	v_mad_u64_u32 v[46:47], s[46:47], v46, s35, v[6:7]
	v_mad_u64_u32 v[48:49], s[46:47], v48, s35, v[6:7]
	v_mad_u64_u32 v[50:51], s[46:47], v50, s35, v[6:7]
	s_waitcnt vmcnt(15)
	ds_write_b32 v20, v9
	s_waitcnt vmcnt(14)
	ds_write_b32 v22, v11
	s_waitcnt vmcnt(13)
	ds_write_b32 v24, v14
	s_waitcnt vmcnt(12)
	ds_write_b32 v26, v19
	s_waitcnt vmcnt(11)
	ds_write_b32 v28, v52
	s_waitcnt vmcnt(10)
	ds_write_b32 v30, v53
	s_waitcnt vmcnt(9)
	ds_write_b32 v32, v54
	s_waitcnt vmcnt(8)
	ds_write_b32 v34, v55
	s_waitcnt vmcnt(7)
	ds_write_b32 v36, v56
	s_waitcnt vmcnt(6)
	ds_write_b32 v38, v57
	s_waitcnt vmcnt(5)
	ds_write_b32 v40, v58
	s_waitcnt vmcnt(4)
	ds_write_b32 v42, v59
	s_waitcnt vmcnt(3)
	ds_write_b32 v44, v60
	s_waitcnt vmcnt(2)
	ds_write_b32 v46, v61
	s_waitcnt vmcnt(1)
	ds_write_b32 v48, v62
	s_waitcnt vmcnt(0)
	ds_write_b32 v50, v63
	s_cbranch_scc1 .LBB0_27
	s_lshl_b32 s28, s28, 6
	s_and_b32 s28, s28, 0x1f00
	s_and_b32 s29, s29, 0x60
	s_or_b32 s28, s28, s29
	s_waitcnt lgkmcnt(0)
	s_and_b32 s2, 0xffff, s2
	s_or_b32 s43, s28, 0x80
	s_lshl_b32 s2, s2, 1
	ds_read2_b32 v[24:25], v15 offset0:33 offset1:41
	ds_read2_b32 v[26:27], v15 offset1:8
	ds_read2_b32 v[28:29], v15 offset0:66 offset1:74
	ds_read2_b32 v[30:31], v15 offset0:99 offset1:107
	ds_read2_b32 v[32:33], v15 offset0:132 offset1:140
	ds_read2_b32 v[34:35], v15 offset0:165 offset1:173
	ds_read2_b32 v[36:37], v15 offset0:198 offset1:206
	ds_read2_b32 v[38:39], v15 offset0:231 offset1:239
	s_add_u32 s28, s38, s2
	s_addc_u32 s29, s39, 0
	v_mov_b32_e32 v11, v5
	v_lshl_add_u64 v[12:13], s[28:29], 0, v[10:11]
	v_or_b32_e32 v3, s43, v7
	v_lshl_add_u64 v[12:13], v[12:13], 0, s[20:21]
	v_lshlrev_b32_e32 v4, 11, v3
	s_waitcnt lgkmcnt(6)
	v_cvt_pk_bf16_f32 v20, v26, v24
	s_waitcnt lgkmcnt(4)
	v_cvt_pk_bf16_f32 v21, v28, v30
	s_waitcnt lgkmcnt(2)
	v_cvt_pk_bf16_f32 v22, v32, v34
	s_waitcnt lgkmcnt(0)
	v_cvt_pk_bf16_f32 v23, v36, v38
	v_lshl_add_u64 v[40:41], v[12:13], 0, v[4:5]
	global_store_dwordx4 v[40:41], v[20:23], off
	v_or_b32_e32 v3, s43, v16
	v_lshlrev_b32_e32 v4, 11, v3
	v_cvt_pk_bf16_f32 v20, v27, v25
	v_cvt_pk_bf16_f32 v21, v29, v31
	v_cvt_pk_bf16_f32 v22, v33, v35
	v_cvt_pk_bf16_f32 v23, v37, v39
	ds_read2_b32 v[26:27], v15 offset0:49 offset1:57
	ds_read2_b32 v[28:29], v15 offset0:16 offset1:24
	ds_read2_b32 v[30:31], v15 offset0:82 offset1:90
	ds_read2_b32 v[32:33], v15 offset0:115 offset1:123
	ds_read2_b32 v[34:35], v15 offset0:148 offset1:156
	ds_read2_b32 v[36:37], v15 offset0:181 offset1:189
	ds_read2_b32 v[38:39], v15 offset0:214 offset1:222
	ds_read2_b32 v[40:41], v15 offset0:247 offset1:255
	v_or_b32_e32 v3, s43, v17
	v_lshl_add_u64 v[24:25], v[12:13], 0, v[4:5]
	v_lshlrev_b32_e32 v4, 11, v3
	v_or_b32_e32 v3, s43, v18
	global_store_dwordx4 v[24:25], v[20:23], off
	v_lshl_add_u64 v[24:25], v[12:13], 0, v[4:5]
	v_lshlrev_b32_e32 v4, 11, v3
	s_waitcnt lgkmcnt(6)
	v_cvt_pk_bf16_f32 v20, v28, v26
	s_waitcnt lgkmcnt(4)
	v_cvt_pk_bf16_f32 v21, v30, v32
	s_waitcnt lgkmcnt(2)
	v_cvt_pk_bf16_f32 v22, v34, v36
	s_waitcnt lgkmcnt(0)
	v_cvt_pk_bf16_f32 v23, v38, v40
	global_store_dwordx4 v[24:25], v[20:23], off
	v_lshl_add_u64 v[12:13], v[12:13], 0, v[4:5]
	s_nop 0
	v_cvt_pk_bf16_f32 v20, v29, v27
	v_cvt_pk_bf16_f32 v21, v31, v33
	v_cvt_pk_bf16_f32 v22, v35, v37
	v_cvt_pk_bf16_f32 v23, v39, v41
	global_store_dwordx4 v[12:13], v[20:23], off
	s_waitcnt lgkmcnt(0)

; #define LAS __attribute__((address_space(3)))
; __device__ __forceinline__ unsigned pk2(float lo, float hi) { return pg8::cvt_pk_bf16(lo, hi); }
; __device__ __forceinline__ void transpose_item(const float* W, int K, int N, bf16* WT, int mode, LAS float* scr, int item, int lane) {
;     const int nblk = N / 32, kb = item / nblk, nb = item % nblk, k0 = 64 * kb, n0 = 32 * nb;
;     int r0 = n0;
;     if (mode == 1) r0 = 256 * (n0 >> 7) + (n0 & 127);
;     else if (mode == 2) r0 = 256 * (n0 >> 7) + 128 + (n0 & 127);
; #pragma unroll 8
;     for (int i = 0; i < 32; ++i) { const int kk = 2 * i + (lane >> 5); scr[kk * 33 + (lane & 31)] = W[(size_t)(k0 + kk) * N + n0 + (lane & 31)]; }
;     asm volatile("s_waitcnt lgkmcnt(0)" ::: "memory");
;     const int c = lane & 7;
; #pragma unroll
;     for (int j = 0; j < 4; ++j) { const int n = (lane >> 3) + 8 * j; const LAS float* s = scr + (8 * c) * 33 + n;
;         u32x4 o; o.x = pk2(s[0 * 33], s[1 * 33]); o.y = pk2(s[2 * 33], s[3 * 33]); o.z = pk2(s[4 * 33], s[5 * 33]); o.w = pk2(s[6 * 33], s[7 * 33]);
;         *(u32x4*)(WT + (size_t)(r0 + n) * K + k0 + 8 * c) = o; }
.LBB0_32:
	s_lshl_b32 s46, s41, 1
	s_lshl_b32 s47, s42, 1
	v_or_b32_e32 v9, s46, v3
	v_or_b32_e32 v11, s47, v4
	s_add_i32 s48, s46, 4
	s_add_i32 s49, s47, 4
	s_add_i32 s50, s46, 8
	s_add_i32 s51, s47, 8
	s_add_i32 s52, s46, 12
	s_add_i32 s53, s47, 12
	s_add_i32 s54, s46, 16
	s_add_i32 s55, s47, 16
	s_add_i32 s56, s46, 20
	s_add_i32 s57, s47, 20
	s_add_i32 s58, s46, 24
	s_add_i32 s59, s47, 24
	s_add_i32 s60, s46, 28
	s_add_i32 s61, s47, 28
	v_mad_u64_u32 v[20:21], s[44:45], v11, s36, v[12:13]
	v_mad_u64_u32 v[22:23], s[44:45], v9, s36, v[12:13]
	v_or_b32_e32 v9, s48, v3
	v_or_b32_e32 v11, s49, v4
	v_or_b32_e32 v14, s50, v3
	v_or_b32_e32 v19, s51, v4
	v_or_b32_e32 v34, s52, v3
	v_or_b32_e32 v32, s53, v4
	v_or_b32_e32 v38, s54, v3
	v_or_b32_e32 v36, s55, v4
	v_or_b32_e32 v42, s56, v3
	v_or_b32_e32 v40, s57, v4
	v_or_b32_e32 v46, s58, v3
	v_or_b32_e32 v44, s59, v4
	v_or_b32_e32 v50, s60, v3
	v_or_b32_e32 v48, s61, v4
	v_mad_u64_u32 v[24:25], s[44:45], v11, s36, v[12:13]
	v_mad_u64_u32 v[26:27], s[44:45], v9, s36, v[12:13]
	v_mad_u64_u32 v[28:29], s[44:45], v19, s36, v[12:13]
	v_mad_u64_u32 v[30:31], s[44:45], v14, s36, v[12:13]
	v_mad_u64_u32 v[32:33], s[44:45], v32, s36, v[12:13]
	v_mad_u64_u32 v[34:35], s[44:45], v34, s36, v[12:13]
	v_mad_u64_u32 v[36:37], s[44:45], v36, s36, v[12:13]
	v_mad_u64_u32 v[38:39], s[44:45], v38, s36, v[12:13]
	v_mad_u64_u32 v[40:41], s[44:45], v40, s36, v[12:13]
	v_mad_u64_u32 v[42:43], s[44:45], v42, s36, v[12:13]
	v_mad_u64_u32 v[44:45], s[44:45], v44, s36, v[12:13]
	v_mad_u64_u32 v[46:47], s[44:45], v46, s36, v[12:13]
	v_mad_u64_u32 v[48:49], s[44:45], v48, s36, v[12:13]
	v_mad_u64_u32 v[50:51], s[44:45], v50, s36, v[12:13]
	global_load_dword v9, v[20:21], off nt
	global_load_dword v11, v[22:23], off nt
	global_load_dword v14, v[24:25], off nt
	global_load_dword v19, v[26:27], off nt
	global_load_dword v52, v[28:29], off nt
	global_load_dword v53, v[30:31], off nt
	global_load_dword v54, v[32:33], off nt
	global_load_dword v55, v[34:35], off nt
	global_load_dword v56, v[36:37], off nt
	global_load_dword v57, v[38:39], off nt
	global_load_dword v58, v[40:41], off nt
	global_load_dword v59, v[42:43], off nt
	global_load_dword v60, v[44:45], off nt
	global_load_dword v61, v[46:47], off nt
	global_load_dword v62, v[48:49], off nt
	global_load_dword v63, v[50:51], off nt
	v_or_b32_e32 v22, s46, v1
	v_or_b32_e32 v20, s47, v2
	s_add_i32 s42, s42, 16
	s_add_i32 s41, s41, 16
	s_add_i32 s43, s43, -16
	v_mad_u64_u32 v[20:21], s[44:45], v20, s35, v[6:7]
	v_mad_u64_u32 v[22:23], s[44:45], v22, s35, v[6:7]
	v_or_b32_e32 v21, s48, v1
	v_or_b32_e32 v23, s49, v2
	v_or_b32_e32 v30, s50, v1
	v_or_b32_e32 v28, s51, v2
	v_or_b32_e32 v34, s52, v1
	v_or_b32_e32 v32, s53, v2
	v_or_b32_e32 v38, s54, v1
	v_or_b32_e32 v36, s55, v2
	v_or_b32_e32 v42, s56, v1
	v_or_b32_e32 v40, s57, v2
	v_or_b32_e32 v46, s58, v1
	v_or_b32_e32 v44, s59, v2
	v_or_b32_e32 v50, s60, v1
	v_or_b32_e32 v48, s61, v2
	s_cmp_lg_u32 s43, 0
	v_mad_u64_u32 v[24:25], s[44:45], v23, s35, v[6:7]
	v_mad_u64_u32 v[26:27], s[44:45], v21, s35, v[6:7]
	v_mad_u64_u32 v[28:29], s[44:45], v28, s35, v[6:7]
	v_mad_u64_u32 v[30:31], s[44:45], v30, s35, v[6:7]
	v_mad_u64_u32 v[32:33], s[44:45], v32, s35, v[6:7]
	v_mad_u64_u32 v[34:35], s[44:45], v34, s35, v[6:7]
	v_mad_u64_u32 v[36:37], s[44:45], v36, s35, v[6:7]
	v_mad_u64_u32 v[38:39], s[44:45], v38, s35, v[6:7]
	v_mad_u64_u32 v[40:41], s[44:45], v40, s35, v[6:7]
	v_mad_u64_u32 v[42:43], s[44:45], v42, s35, v[6:7]
	v_mad_u64_u32 v[44:45], s[44:45], v44, s35, v[6:7]
	v_mad_u64_u32 v[46:47], s[44:45], v46, s35, v[6:7]
	v_mad_u64_u32 v[48:49], s[44:45], v48, s35, v[6:7]
	v_mad_u64_u32 v[50:51], s[44:45], v50, s35, v[6:7]
	s_waitcnt vmcnt(15)
	ds_write_b32 v20, v9
	s_waitcnt vmcnt(14)
	ds_write_b32 v22, v11
	s_waitcnt vmcnt(13)
	ds_write_b32 v24, v14
	s_waitcnt vmcnt(12)
	ds_write_b32 v26, v19
	s_waitcnt vmcnt(11)
	ds_write_b32 v28, v52
	s_waitcnt vmcnt(10)
	ds_write_b32 v30, v53
	s_waitcnt vmcnt(9)
	ds_write_b32 v32, v54
	s_waitcnt vmcnt(8)
	ds_write_b32 v34, v55
	s_waitcnt vmcnt(7)
	ds_write_b32 v36, v56
	s_waitcnt vmcnt(6)
	ds_write_b32 v38, v57
	s_waitcnt vmcnt(5)
	ds_write_b32 v40, v58
	s_waitcnt vmcnt(4)
	ds_write_b32 v42, v59
	s_waitcnt vmcnt(3)
	ds_write_b32 v44, v60
	s_waitcnt vmcnt(2)
	ds_write_b32 v46, v61
	s_waitcnt vmcnt(1)
	ds_write_b32 v48, v62
	s_waitcnt vmcnt(0)
	ds_write_b32 v50, v63
	s_cbranch_scc1 .LBB0_32
	s_lshl_b32 s28, s28, 6
	s_and_b32 s29, s29, 0x60
	s_and_b32 s28, s28, 0x1f00
	s_waitcnt lgkmcnt(0)
	s_and_b32 s2, 0xffff, s2
	s_or_b32 s41, s28, s29
	s_lshl_b32 s2, s2, 1
	ds_read2_b32 v[24:25], v15 offset0:33 offset1:41
	ds_read2_b32 v[26:27], v15 offset1:8
	ds_read2_b32 v[28:29], v15 offset0:66 offset1:74
	ds_read2_b32 v[30:31], v15 offset0:99 offset1:107
	ds_read2_b32 v[32:33], v15 offset0:132 offset1:140
	ds_read2_b32 v[34:35], v15 offset0:165 offset1:173
	ds_read2_b32 v[36:37], v15 offset0:198 offset1:206
	ds_read2_b32 v[38:39], v15 offset0:231 offset1:239
	s_add_u32 s28, s38, s2
	s_addc_u32 s29, s39, 0
	v_mov_b32_e32 v11, v5
	v_lshl_add_u64 v[12:13], s[28:29], 0, v[10:11]
	v_or_b32_e32 v3, s41, v7
	v_lshl_add_u64 v[12:13], v[12:13], 0, s[20:21]
	v_lshlrev_b32_e32 v4, 11, v3
	s_waitcnt lgkmcnt(6)
	v_cvt_pk_bf16_f32 v20, v26, v24
	s_waitcnt lgkmcnt(4)
	v_cvt_pk_bf16_f32 v21, v28, v30
	s_waitcnt lgkmcnt(2)
	v_cvt_pk_bf16_f32 v22, v32, v34
	s_waitcnt lgkmcnt(0)
	v_cvt_pk_bf16_f32 v23, v36, v38
	v_lshl_add_u64 v[40:41], v[12:13], 0, v[4:5]
	global_store_dwordx4 v[40:41], v[20:23], off
	v_or_b32_e32 v3, s41, v16
	v_lshlrev_b32_e32 v4, 11, v3
	v_cvt_pk_bf16_f32 v20, v27, v25
	v_cvt_pk_bf16_f32 v21, v29, v31
	v_cvt_pk_bf16_f32 v22, v33, v35
	v_cvt_pk_bf16_f32 v23, v37, v39
	ds_read2_b32 v[26:27], v15 offset0:49 offset1:57
	ds_read2_b32 v[28:29], v15 offset0:16 offset1:24
	ds_read2_b32 v[30:31], v15 offset0:82 offset1:90
	ds_read2_b32 v[32:33], v15 offset0:115 offset1:123
	ds_read2_b32 v[34:35], v15 offset0:148 offset1:156
	ds_read2_b32 v[36:37], v15 offset0:181 offset1:189
	ds_read2_b32 v[38:39], v15 offset0:214 offset1:222
	ds_read2_b32 v[40:41], v15 offset0:247 offset1:255
	v_or_b32_e32 v3, s41, v17
	v_lshl_add_u64 v[24:25], v[12:13], 0, v[4:5]
	v_lshlrev_b32_e32 v4, 11, v3
	v_or_b32_e32 v3, s41, v18
	global_store_dwordx4 v[24:25], v[20:23], off
	v_lshl_add_u64 v[24:25], v[12:13], 0, v[4:5]
	v_lshlrev_b32_e32 v4, 11, v3
	s_waitcnt lgkmcnt(6)
	v_cvt_pk_bf16_f32 v20, v28, v26
	s_waitcnt lgkmcnt(4)
	v_cvt_pk_bf16_f32 v21, v30, v32
	s_waitcnt lgkmcnt(2)
	v_cvt_pk_bf16_f32 v22, v34, v36
	s_waitcnt lgkmcnt(0)
	v_cvt_pk_bf16_f32 v23, v38, v40
	global_store_dwordx4 v[24:25], v[20:23], off
	v_lshl_add_u64 v[12:13], v[12:13], 0, v[4:5]
	s_nop 0
	v_cvt_pk_bf16_f32 v20, v29, v27
	v_cvt_pk_bf16_f32 v21, v31, v33
	v_cvt_pk_bf16_f32 v22, v35, v37
	v_cvt_pk_bf16_f32 v23, v39, v41
	global_store_dwordx4 v[12:13], v[20:23], off
	s_waitcnt lgkmcnt(0)

; __device__ __forceinline__ void transpose_item(const float* W, int K, int N, bf16* WT, int mode, LAS float* scr, int item, int lane) {
;     ...
; #pragma unroll 8
;     for (int i = 0; i < 32; ++i) { const int kk = 2 * i + (lane >> 5); scr[kk * 33 + (lane & 31)] = W[(size_t)(k0 + kk) * N + n0 + (lane & 31)]; }
.LBB0_37:
	s_lshl_b32 s43, s28, 1
	s_lshl_b32 s44, s41, 1
	v_or_b32_e32 v4, s44, v14
	s_add_i32 s46, s43, 4
	s_add_i32 s47, s44, 4
	v_mov_b32_e32 v23, v5
	s_add_i32 s49, s44, 8
	v_lshlrev_b64 v[36:37], 12, v[4:5]
	v_or_b32_e32 v22, s46, v3
	v_or_b32_e32 v4, s47, v14
	v_mov_b32_e32 v21, v5
	v_or_b32_e32 v20, s43, v3
	s_add_i32 s51, s44, 12
	v_lshlrev_b64 v[22:23], 12, v[22:23]
	v_lshlrev_b64 v[38:39], 12, v[4:5]
	v_or_b32_e32 v4, s49, v14
	s_add_i32 s48, s43, 8
	s_add_i32 s50, s43, 12
	s_add_i32 s53, s44, 16
	v_lshlrev_b64 v[20:21], 12, v[20:21]
	v_lshl_add_u64 v[36:37], v[12:13], 0, v[36:37]
	v_lshl_add_u64 v[22:23], v[12:13], 0, v[22:23]
	v_lshlrev_b64 v[40:41], 12, v[4:5]
	v_or_b32_e32 v4, s51, v14
	v_mov_b32_e32 v25, v5
	v_mov_b32_e32 v27, v5
	s_add_i32 s55, s44, 20
	v_or_b32_e32 v24, s48, v3
	v_or_b32_e32 v26, s50, v3
	v_lshl_add_u64 v[20:21], v[12:13], 0, v[20:21]
	v_lshl_add_u64 v[38:39], v[12:13], 0, v[38:39]
	global_load_dword v9, v[36:37], off nt
	global_load_dword v11, v[20:21], off nt
	global_load_dword v19, v[38:39], off nt
	global_load_dword v52, v[22:23], off nt
	v_lshlrev_b64 v[22:23], 12, v[4:5]
	v_or_b32_e32 v4, s53, v14
	s_add_i32 s52, s43, 16
	s_add_i32 s54, s43, 20
	s_add_i32 s57, s44, 24
	v_lshlrev_b64 v[24:25], 12, v[24:25]
	v_lshlrev_b64 v[26:27], 12, v[26:27]
	v_lshl_add_u64 v[20:21], v[12:13], 0, v[40:41]
	v_lshl_add_u64 v[22:23], v[12:13], 0, v[22:23]
	v_lshlrev_b64 v[36:37], 12, v[4:5]
	v_or_b32_e32 v4, s55, v14
	v_mov_b32_e32 v29, v5
	v_mov_b32_e32 v31, v5
	s_add_i32 s56, s43, 24
	s_add_i32 s58, s43, 28
	s_add_i32 s59, s44, 28
	v_or_b32_e32 v28, s52, v3
	v_or_b32_e32 v30, s54, v3
	v_lshl_add_u64 v[24:25], v[12:13], 0, v[24:25]
	v_lshl_add_u64 v[26:27], v[12:13], 0, v[26:27]
	global_load_dword v53, v[20:21], off nt
	global_load_dword v54, v[24:25], off nt
	global_load_dword v55, v[22:23], off nt
	global_load_dword v56, v[26:27], off nt
	v_lshlrev_b64 v[22:23], 12, v[4:5]
	v_or_b32_e32 v4, s57, v14
	v_mov_b32_e32 v33, v5
	v_mov_b32_e32 v35, v5
	v_or_b32_e32 v32, s56, v3
	v_or_b32_e32 v34, s58, v3
	v_lshlrev_b64 v[28:29], 12, v[28:29]
	v_lshlrev_b64 v[30:31], 12, v[30:31]
	v_lshl_add_u64 v[20:21], v[12:13], 0, v[36:37]
	v_lshl_add_u64 v[22:23], v[12:13], 0, v[22:23]
	v_lshlrev_b64 v[24:25], 12, v[4:5]
	v_or_b32_e32 v4, s59, v14
	v_lshlrev_b64 v[32:33], 12, v[32:33]
	v_lshlrev_b64 v[34:35], 12, v[34:35]
	v_lshl_add_u64 v[28:29], v[12:13], 0, v[28:29]
	v_lshl_add_u64 v[30:31], v[12:13], 0, v[30:31]
	global_load_dword v57, v[20:21], off nt
	global_load_dword v58, v[28:29], off nt
	global_load_dword v59, v[22:23], off nt
	global_load_dword v60, v[30:31], off nt
	v_lshl_add_u64 v[20:21], v[12:13], 0, v[24:25]
	v_lshlrev_b64 v[22:23], 12, v[4:5]
	v_lshl_add_u64 v[32:33], v[12:13], 0, v[32:33]
	v_lshl_add_u64 v[34:35], v[12:13], 0, v[34:35]
	v_lshl_add_u64 v[22:23], v[12:13], 0, v[22:23]
	global_load_dword v4, v[20:21], off nt
	global_load_dword v61, v[32:33], off nt
	global_load_dword v62, v[22:23], off nt
	global_load_dword v63, v[34:35], off nt
	v_or_b32_e32 v22, s43, v1
	v_or_b32_e32 v20, s44, v2
	s_add_i32 s41, s41, 16
	s_add_i32 s28, s28, 16
	s_add_i32 s42, s42, -16
	v_mad_u64_u32 v[20:21], s[44:45], v20, s35, v[6:7]
	v_mad_u64_u32 v[22:23], s[44:45], v22, s35, v[6:7]
	v_or_b32_e32 v21, s46, v1
	v_or_b32_e32 v23, s47, v2
	v_or_b32_e32 v30, s48, v1
	v_or_b32_e32 v28, s49, v2
	v_or_b32_e32 v34, s50, v1
	v_or_b32_e32 v32, s51, v2
	v_or_b32_e32 v38, s52, v1
	v_or_b32_e32 v36, s53, v2
	v_or_b32_e32 v42, s54, v1
	v_or_b32_e32 v40, s55, v2
	v_or_b32_e32 v46, s56, v1
	v_or_b32_e32 v44, s57, v2
	v_or_b32_e32 v50, s58, v1
	v_or_b32_e32 v48, s59, v2
	s_cmp_lg_u32 s42, 0
	v_mad_u64_u32 v[24:25], s[44:45], v23, s35, v[6:7]
	v_mad_u64_u32 v[26:27], s[44:45], v21, s35, v[6:7]
	v_mad_u64_u32 v[28:29], s[44:45], v28, s35, v[6:7]
	v_mad_u64_u32 v[30:31], s[44:45], v30, s35, v[6:7]
	v_mad_u64_u32 v[32:33], s[44:45], v32, s35, v[6:7]
	v_mad_u64_u32 v[34:35], s[44:45], v34, s35, v[6:7]
	v_mad_u64_u32 v[36:37], s[44:45], v36, s35, v[6:7]
	v_mad_u64_u32 v[38:39], s[44:45], v38, s35, v[6:7]
	v_mad_u64_u32 v[40:41], s[44:45], v40, s35, v[6:7]
	v_mad_u64_u32 v[42:43], s[44:45], v42, s35, v[6:7]
	v_mad_u64_u32 v[44:45], s[44:45], v44, s35, v[6:7]
	v_mad_u64_u32 v[46:47], s[44:45], v46, s35, v[6:7]
	v_mad_u64_u32 v[48:49], s[44:45], v48, s35, v[6:7]
	v_mad_u64_u32 v[50:51], s[44:45], v50, s35, v[6:7]
	s_waitcnt vmcnt(15)
	ds_write_b32 v20, v9
	s_waitcnt vmcnt(14)
	ds_write_b32 v22, v11
	s_waitcnt vmcnt(13)
	ds_write_b32 v24, v19
	s_waitcnt vmcnt(12)
	ds_write_b32 v26, v52
	s_waitcnt vmcnt(11)
	ds_write_b32 v28, v53
	s_waitcnt vmcnt(10)
	ds_write_b32 v30, v54
	s_waitcnt vmcnt(9)
	ds_write_b32 v32, v55
	s_waitcnt vmcnt(8)
	ds_write_b32 v34, v56
	s_waitcnt vmcnt(7)
	ds_write_b32 v36, v57
	s_waitcnt vmcnt(6)
	ds_write_b32 v38, v58
	s_waitcnt vmcnt(5)
	ds_write_b32 v40, v59
	s_waitcnt vmcnt(4)
	ds_write_b32 v42, v60
	s_waitcnt vmcnt(3)
	ds_write_b32 v44, v4
	s_waitcnt vmcnt(2)
	ds_write_b32 v46, v61
	s_waitcnt vmcnt(1)
	ds_write_b32 v48, v62
	s_waitcnt vmcnt(0)
	ds_write_b32 v50, v63
	s_cbranch_scc1 .LBB0_37
; #define LAS __attribute__((address_space(3)))
; __device__ __forceinline__ unsigned pk2(float lo, float hi) { return pg8::cvt_pk_bf16(lo, hi); }
; __device__ __forceinline__ void transpose_item(const float* W, int K, int N, bf16* WT, int mode, LAS float* scr, int item, int lane) {
;     ...
;     const int c = lane & 7;
; #pragma unroll
;     for (int j = 0; j < 4; ++j) { const int n = (lane >> 3) + 8 * j; const LAS float* s = scr + (8 * c) * 33 + n;
;         u32x4 o; o.x = pk2(s[0 * 33], s[1 * 33]); o.y = pk2(s[2 * 33], s[3 * 33]); o.z = pk2(s[4 * 33], s[5 * 33]); o.w = pk2(s[6 * 33], s[7 * 33]);
;         *(u32x4*)(WT + (size_t)(r0 + n) * K + k0 + 8 * c) = o; }
;     asm volatile("s_waitcnt lgkmcnt(0)" ::: "memory");
	s_waitcnt lgkmcnt(0)
	s_lshl_b32 s28, s29, 1
	ds_read2_b32 v[24:25], v15 offset0:33 offset1:41
	ds_read2_b32 v[26:27], v15 offset1:8
	ds_read2_b32 v[28:29], v15 offset0:66 offset1:74
	ds_read2_b32 v[30:31], v15 offset0:99 offset1:107
	ds_read2_b32 v[32:33], v15 offset0:132 offset1:140
	ds_read2_b32 v[34:35], v15 offset0:165 offset1:173
	ds_read2_b32 v[36:37], v15 offset0:198 offset1:206
	ds_read2_b32 v[38:39], v15 offset0:231 offset1:239
	s_add_u32 s28, s38, s28
	s_addc_u32 s29, s39, 0
	v_mov_b32_e32 v11, v5
	v_lshl_add_u64 v[12:13], s[28:29], 0, v[10:11]
	v_or_b32_e32 v3, s2, v7
	v_lshl_add_u64 v[12:13], v[12:13], 0, s[22:23]
	v_lshlrev_b32_e32 v4, 11, v3
	s_waitcnt lgkmcnt(6)
	v_cvt_pk_bf16_f32 v20, v26, v24
	s_waitcnt lgkmcnt(4)
	v_cvt_pk_bf16_f32 v21, v28, v30
	s_waitcnt lgkmcnt(2)
	v_cvt_pk_bf16_f32 v22, v32, v34
	s_waitcnt lgkmcnt(0)
	v_cvt_pk_bf16_f32 v23, v36, v38
	v_lshl_add_u64 v[40:41], v[12:13], 0, v[4:5]
	global_store_dwordx4 v[40:41], v[20:23], off
	v_or_b32_e32 v3, s2, v16
	v_lshlrev_b32_e32 v4, 11, v3
	v_cvt_pk_bf16_f32 v20, v27, v25
	v_cvt_pk_bf16_f32 v21, v29, v31
	v_cvt_pk_bf16_f32 v22, v33, v35
	v_cvt_pk_bf16_f32 v23, v37, v39
	ds_read2_b32 v[26:27], v15 offset0:49 offset1:57
	ds_read2_b32 v[28:29], v15 offset0:16 offset1:24
	ds_read2_b32 v[30:31], v15 offset0:82 offset1:90
	ds_read2_b32 v[32:33], v15 offset0:115 offset1:123
	ds_read2_b32 v[34:35], v15 offset0:148 offset1:156
	ds_read2_b32 v[36:37], v15 offset0:181 offset1:189
	ds_read2_b32 v[38:39], v15 offset0:214 offset1:222
	ds_read2_b32 v[40:41], v15 offset0:247 offset1:255
	v_or_b32_e32 v3, s2, v17
	v_lshl_add_u64 v[24:25], v[12:13], 0, v[4:5]
	v_lshlrev_b32_e32 v4, 11, v3
	v_or_b32_e32 v3, s2, v18
	global_store_dwordx4 v[24:25], v[20:23], off
	v_lshl_add_u64 v[24:25], v[12:13], 0, v[4:5]
	v_lshlrev_b32_e32 v4, 11, v3
	s_waitcnt lgkmcnt(6)
	v_cvt_pk_bf16_f32 v20, v28, v26
	s_waitcnt lgkmcnt(4)
	v_cvt_pk_bf16_f32 v21, v30, v32
	s_waitcnt lgkmcnt(2)
	v_cvt_pk_bf16_f32 v22, v34, v36
	s_waitcnt lgkmcnt(0)
	v_cvt_pk_bf16_f32 v23, v38, v40
	global_store_dwordx4 v[24:25], v[20:23], off
	v_lshl_add_u64 v[12:13], v[12:13], 0, v[4:5]
	s_nop 0
	v_cvt_pk_bf16_f32 v20, v29, v27
	v_cvt_pk_bf16_f32 v21, v31, v33
	v_cvt_pk_bf16_f32 v22, v35, v37
	v_cvt_pk_bf16_f32 v23, v39, v41
	global_store_dwordx4 v[12:13], v[20:23], off
	s_waitcnt lgkmcnt(0)

; __device__ __forceinline__ void transpose_item(const float* W, int K, int N, bf16* WT, int mode, LAS float* scr, int item, int lane) {
;     ...
; #pragma unroll 8
;     for (int i = 0; i < 32; ++i) { const int kk = 2 * i + (lane >> 5); scr[kk * 33 + (lane & 31)] = W[(size_t)(k0 + kk) * N + n0 + (lane & 31)]; }
.LBB0_42:
	s_lshl_b32 s43, s28, 1
	s_lshl_b32 s44, s41, 1
	v_or_b32_e32 v4, s44, v14
	s_add_i32 s46, s43, 4
	s_add_i32 s47, s44, 4
	v_mov_b32_e32 v23, v5
	s_add_i32 s49, s44, 8
	v_lshlrev_b64 v[36:37], 12, v[4:5]
	v_or_b32_e32 v22, s46, v3
	v_or_b32_e32 v4, s47, v14
	v_mov_b32_e32 v21, v5
	v_or_b32_e32 v20, s43, v3
	s_add_i32 s51, s44, 12
	v_lshlrev_b64 v[22:23], 12, v[22:23]
	v_lshlrev_b64 v[38:39], 12, v[4:5]
	v_or_b32_e32 v4, s49, v14
	s_add_i32 s48, s43, 8
	s_add_i32 s50, s43, 12
	s_add_i32 s53, s44, 16
	v_lshlrev_b64 v[20:21], 12, v[20:21]
	v_lshl_add_u64 v[36:37], v[12:13], 0, v[36:37]
	v_lshl_add_u64 v[22:23], v[12:13], 0, v[22:23]
	v_lshlrev_b64 v[40:41], 12, v[4:5]
	v_or_b32_e32 v4, s51, v14
	v_mov_b32_e32 v25, v5
	v_mov_b32_e32 v27, v5
	s_add_i32 s55, s44, 20
	v_or_b32_e32 v24, s48, v3
	v_or_b32_e32 v26, s50, v3
	v_lshl_add_u64 v[20:21], v[12:13], 0, v[20:21]
	v_lshl_add_u64 v[38:39], v[12:13], 0, v[38:39]
	global_load_dword v9, v[36:37], off nt
	global_load_dword v11, v[20:21], off nt
	global_load_dword v19, v[38:39], off nt
	global_load_dword v52, v[22:23], off nt
	v_lshlrev_b64 v[22:23], 12, v[4:5]
	v_or_b32_e32 v4, s53, v14
	s_add_i32 s52, s43, 16
	s_add_i32 s54, s43, 20
	s_add_i32 s57, s44, 24
	v_lshlrev_b64 v[24:25], 12, v[24:25]
	v_lshlrev_b64 v[26:27], 12, v[26:27]
	v_lshl_add_u64 v[20:21], v[12:13], 0, v[40:41]
	v_lshl_add_u64 v[22:23], v[12:13], 0, v[22:23]
	v_lshlrev_b64 v[36:37], 12, v[4:5]
	v_or_b32_e32 v4, s55, v14
	v_mov_b32_e32 v29, v5
	v_mov_b32_e32 v31, v5
	s_add_i32 s56, s43, 24
	s_add_i32 s58, s43, 28
	s_add_i32 s59, s44, 28
	v_or_b32_e32 v28, s52, v3
	v_or_b32_e32 v30, s54, v3
	v_lshl_add_u64 v[24:25], v[12:13], 0, v[24:25]
	v_lshl_add_u64 v[26:27], v[12:13], 0, v[26:27]
	global_load_dword v53, v[20:21], off nt
	global_load_dword v54, v[24:25], off nt
	global_load_dword v55, v[22:23], off nt
	global_load_dword v56, v[26:27], off nt
	v_lshlrev_b64 v[22:23], 12, v[4:5]
	v_or_b32_e32 v4, s57, v14
	v_mov_b32_e32 v33, v5
	v_mov_b32_e32 v35, v5
	v_or_b32_e32 v32, s56, v3
	v_or_b32_e32 v34, s58, v3
	v_lshlrev_b64 v[28:29], 12, v[28:29]
	v_lshlrev_b64 v[30:31], 12, v[30:31]
	v_lshl_add_u64 v[20:21], v[12:13], 0, v[36:37]
	v_lshl_add_u64 v[22:23], v[12:13], 0, v[22:23]
	v_lshlrev_b64 v[24:25], 12, v[4:5]
	v_or_b32_e32 v4, s59, v14
	v_lshlrev_b64 v[32:33], 12, v[32:33]
	v_lshlrev_b64 v[34:35], 12, v[34:35]
	v_lshl_add_u64 v[28:29], v[12:13], 0, v[28:29]
	v_lshl_add_u64 v[30:31], v[12:13], 0, v[30:31]
	global_load_dword v57, v[20:21], off nt
	global_load_dword v58, v[28:29], off nt
	global_load_dword v59, v[22:23], off nt
	global_load_dword v60, v[30:31], off nt
	v_lshl_add_u64 v[20:21], v[12:13], 0, v[24:25]
	v_lshlrev_b64 v[22:23], 12, v[4:5]
	v_lshl_add_u64 v[32:33], v[12:13], 0, v[32:33]
	v_lshl_add_u64 v[34:35], v[12:13], 0, v[34:35]
	v_lshl_add_u64 v[22:23], v[12:13], 0, v[22:23]
	global_load_dword v4, v[20:21], off nt
	global_load_dword v61, v[32:33], off nt
	global_load_dword v62, v[22:23], off nt
	global_load_dword v63, v[34:35], off nt
	v_or_b32_e32 v22, s43, v1
	v_or_b32_e32 v20, s44, v2
	s_add_i32 s41, s41, 16
	s_add_i32 s28, s28, 16
	s_add_i32 s42, s42, -16
	v_mad_u64_u32 v[20:21], s[44:45], v20, s35, v[6:7]
	v_mad_u64_u32 v[22:23], s[44:45], v22, s35, v[6:7]
	v_or_b32_e32 v21, s46, v1
	v_or_b32_e32 v23, s47, v2
	v_or_b32_e32 v30, s48, v1
	v_or_b32_e32 v28, s49, v2
	v_or_b32_e32 v34, s50, v1
	v_or_b32_e32 v32, s51, v2
	v_or_b32_e32 v38, s52, v1
	v_or_b32_e32 v36, s53, v2
	v_or_b32_e32 v42, s54, v1
	v_or_b32_e32 v40, s55, v2
	v_or_b32_e32 v46, s56, v1
	v_or_b32_e32 v44, s57, v2
	v_or_b32_e32 v50, s58, v1
	v_or_b32_e32 v48, s59, v2
	s_cmp_lg_u32 s42, 0
	v_mad_u64_u32 v[24:25], s[44:45], v23, s35, v[6:7]
	v_mad_u64_u32 v[26:27], s[44:45], v21, s35, v[6:7]
	v_mad_u64_u32 v[28:29], s[44:45], v28, s35, v[6:7]
	v_mad_u64_u32 v[30:31], s[44:45], v30, s35, v[6:7]
	v_mad_u64_u32 v[32:33], s[44:45], v32, s35, v[6:7]
	v_mad_u64_u32 v[34:35], s[44:45], v34, s35, v[6:7]
	v_mad_u64_u32 v[36:37], s[44:45], v36, s35, v[6:7]
	v_mad_u64_u32 v[38:39], s[44:45], v38, s35, v[6:7]
	v_mad_u64_u32 v[40:41], s[44:45], v40, s35, v[6:7]
	v_mad_u64_u32 v[42:43], s[44:45], v42, s35, v[6:7]
	v_mad_u64_u32 v[44:45], s[44:45], v44, s35, v[6:7]
	v_mad_u64_u32 v[46:47], s[44:45], v46, s35, v[6:7]
	v_mad_u64_u32 v[48:49], s[44:45], v48, s35, v[6:7]
	v_mad_u64_u32 v[50:51], s[44:45], v50, s35, v[6:7]
	s_waitcnt vmcnt(15)
	ds_write_b32 v20, v9
	s_waitcnt vmcnt(14)
	ds_write_b32 v22, v11
	s_waitcnt vmcnt(13)
	ds_write_b32 v24, v19
	s_waitcnt vmcnt(12)
	ds_write_b32 v26, v52
	s_waitcnt vmcnt(11)
	ds_write_b32 v28, v53
	s_waitcnt vmcnt(10)
	ds_write_b32 v30, v54
	s_waitcnt vmcnt(9)
	ds_write_b32 v32, v55
	s_waitcnt vmcnt(8)
	ds_write_b32 v34, v56
	s_waitcnt vmcnt(7)
	ds_write_b32 v36, v57
	s_waitcnt vmcnt(6)
	ds_write_b32 v38, v58
	s_waitcnt vmcnt(5)
	ds_write_b32 v40, v59
	s_waitcnt vmcnt(4)
	ds_write_b32 v42, v60
	s_waitcnt vmcnt(3)
	ds_write_b32 v44, v4
	s_waitcnt vmcnt(2)
	ds_write_b32 v46, v61
	s_waitcnt vmcnt(1)
	ds_write_b32 v48, v62
	s_waitcnt vmcnt(0)
	ds_write_b32 v50, v63
	s_cbranch_scc1 .LBB0_42
; #define LAS __attribute__((address_space(3)))
; __device__ __forceinline__ unsigned pk2(float lo, float hi) { return pg8::cvt_pk_bf16(lo, hi); }
; __device__ __forceinline__ void transpose_item(const float* W, int K, int N, bf16* WT, int mode, LAS float* scr, int item, int lane) {
;     ...
;     const int c = lane & 7;
; #pragma unroll
;     for (int j = 0; j < 4; ++j) { const int n = (lane >> 3) + 8 * j; const LAS float* s = scr + (8 * c) * 33 + n;
;         u32x4 o; o.x = pk2(s[0 * 33], s[1 * 33]); o.y = pk2(s[2 * 33], s[3 * 33]); o.z = pk2(s[4 * 33], s[5 * 33]); o.w = pk2(s[6 * 33], s[7 * 33]);
;         *(u32x4*)(WT + (size_t)(r0 + n) * K + k0 + 8 * c) = o; }
;     asm volatile("s_waitcnt lgkmcnt(0)" ::: "memory");
	s_lshl_b64 s[42:43], s[2:3], 20
	s_add_u32 s2, s38, s42
	s_waitcnt lgkmcnt(0)
	s_addc_u32 s41, s39, s43
	s_lshl_b32 s28, s29, 1
	ds_read2_b32 v[24:25], v15 offset0:33 offset1:41
	ds_read2_b32 v[26:27], v15 offset1:8
	ds_read2_b32 v[28:29], v15 offset0:66 offset1:74
	ds_read2_b32 v[30:31], v15 offset0:99 offset1:107
	ds_read2_b32 v[32:33], v15 offset0:132 offset1:140
	ds_read2_b32 v[34:35], v15 offset0:165 offset1:173
	ds_read2_b32 v[36:37], v15 offset0:198 offset1:206
	ds_read2_b32 v[38:39], v15 offset0:231 offset1:239
	s_add_u32 s28, s2, s28
	s_addc_u32 s29, s41, 0
	v_mov_b32_e32 v11, v5
	v_lshl_add_u64 v[12:13], s[28:29], 0, v[10:11]
	v_or_b32_e32 v3, s27, v7
	v_lshl_add_u64 v[12:13], v[12:13], 0, s[24:25]
	v_lshlrev_b32_e32 v4, 10, v3
	s_waitcnt lgkmcnt(6)
	v_cvt_pk_bf16_f32 v20, v26, v24
	s_waitcnt lgkmcnt(4)
	v_cvt_pk_bf16_f32 v21, v28, v30
	s_waitcnt lgkmcnt(2)
	v_cvt_pk_bf16_f32 v22, v32, v34
	s_waitcnt lgkmcnt(0)
	v_cvt_pk_bf16_f32 v23, v36, v38
	v_lshl_add_u64 v[40:41], v[12:13], 0, v[4:5]
	global_store_dwordx4 v[40:41], v[20:23], off
	v_or_b32_e32 v3, s27, v16
	v_lshlrev_b32_e32 v4, 10, v3
	v_cvt_pk_bf16_f32 v20, v27, v25
	v_cvt_pk_bf16_f32 v21, v29, v31
	v_cvt_pk_bf16_f32 v22, v33, v35
	v_cvt_pk_bf16_f32 v23, v37, v39
	ds_read2_b32 v[26:27], v15 offset0:49 offset1:57
	ds_read2_b32 v[28:29], v15 offset0:16 offset1:24
	ds_read2_b32 v[30:31], v15 offset0:82 offset1:90
	ds_read2_b32 v[32:33], v15 offset0:115 offset1:123
	ds_read2_b32 v[34:35], v15 offset0:148 offset1:156
	ds_read2_b32 v[36:37], v15 offset0:181 offset1:189
	ds_read2_b32 v[38:39], v15 offset0:214 offset1:222
	ds_read2_b32 v[40:41], v15 offset0:247 offset1:255
	v_or_b32_e32 v3, s27, v17
	v_lshl_add_u64 v[24:25], v[12:13], 0, v[4:5]
	v_lshlrev_b32_e32 v4, 10, v3
	v_or_b32_e32 v3, s27, v18
	global_store_dwordx4 v[24:25], v[20:23], off
	v_lshl_add_u64 v[24:25], v[12:13], 0, v[4:5]
	v_lshlrev_b32_e32 v4, 10, v3
	s_waitcnt lgkmcnt(6)
	v_cvt_pk_bf16_f32 v20, v28, v26
	s_waitcnt lgkmcnt(4)
	v_cvt_pk_bf16_f32 v21, v30, v32
	s_waitcnt lgkmcnt(2)
	v_cvt_pk_bf16_f32 v22, v34, v36
	s_waitcnt lgkmcnt(0)
	v_cvt_pk_bf16_f32 v23, v38, v40
	global_store_dwordx4 v[24:25], v[20:23], off
	v_lshl_add_u64 v[12:13], v[12:13], 0, v[4:5]
	s_nop 0
	v_cvt_pk_bf16_f32 v20, v29, v27
	v_cvt_pk_bf16_f32 v21, v31, v33
	v_cvt_pk_bf16_f32 v22, v35, v37
	v_cvt_pk_bf16_f32 v23, v39, v41
	global_store_dwordx4 v[12:13], v[20:23], off
	s_waitcnt lgkmcnt(0)

; #define LAS __attribute__((address_space(3)))
; __device__ __forceinline__ unsigned pk2(float lo, float hi) { return pg8::cvt_pk_bf16(lo, hi); }
; __device__ __forceinline__ void transpose_item(const float* W, int K, int N, bf16* WT, int mode, LAS float* scr, int item, int lane) {
;     const int nblk = N / 32, kb = item / nblk, nb = item % nblk, k0 = 64 * kb, n0 = 32 * nb;
;     int r0 = n0;
;     if (mode == 1) r0 = 256 * (n0 >> 7) + (n0 & 127);
;     else if (mode == 2) r0 = 256 * (n0 >> 7) + 128 + (n0 & 127);
; #pragma unroll 8
;     for (int i = 0; i < 32; ++i) { const int kk = 2 * i + (lane >> 5); scr[kk * 33 + (lane & 31)] = W[(size_t)(k0 + kk) * N + n0 + (lane & 31)]; }
;     asm volatile("s_waitcnt lgkmcnt(0)" ::: "memory");
;     const int c = lane & 7;
; #pragma unroll
;     for (int j = 0; j < 4; ++j) { const int n = (lane >> 3) + 8 * j; const LAS float* s = scr + (8 * c) * 33 + n;
;         u32x4 o; o.x = pk2(s[0 * 33], s[1 * 33]); o.y = pk2(s[2 * 33], s[3 * 33]); o.z = pk2(s[4 * 33], s[5 * 33]); o.w = pk2(s[6 * 33], s[7 * 33]);
;         *(u32x4*)(WT + (size_t)(r0 + n) * K + k0 + 8 * c) = o; }
;     asm volatile("s_waitcnt lgkmcnt(0)" ::: "memory");
.LBB0_46:
	s_lshl_b32 s42, s2, 1
	s_lshl_b32 s43, s27, 1
	v_or_b32_e32 v9, s42, v3
	v_or_b32_e32 v11, s43, v4
	s_add_i32 s44, s42, 4
	s_add_i32 s45, s43, 4
	s_add_i32 s46, s42, 8
	s_add_i32 s47, s43, 8
	s_add_i32 s48, s42, 12
	s_add_i32 s49, s43, 12
	s_add_i32 s50, s42, 16
	s_add_i32 s51, s43, 16
	s_add_i32 s52, s42, 20
	s_add_i32 s53, s43, 20
	s_add_i32 s54, s42, 24
	s_add_i32 s55, s43, 24
	s_add_i32 s56, s42, 28
	s_add_i32 s57, s43, 28
	v_mad_i64_i32 v[20:21], s[40:41], v11, s37, v[12:13]
	v_mad_i64_i32 v[22:23], s[40:41], v9, s37, v[12:13]
	v_or_b32_e32 v9, s44, v3
	v_or_b32_e32 v11, s45, v4
	v_or_b32_e32 v14, s46, v3
	v_or_b32_e32 v19, s47, v4
	v_or_b32_e32 v34, s48, v3
	v_or_b32_e32 v32, s49, v4
	v_or_b32_e32 v38, s50, v3
	v_or_b32_e32 v36, s51, v4
	v_or_b32_e32 v42, s52, v3
	v_or_b32_e32 v40, s53, v4
	v_or_b32_e32 v46, s54, v3
	v_or_b32_e32 v44, s55, v4
	v_or_b32_e32 v50, s56, v3
	v_or_b32_e32 v48, s57, v4
	v_mad_i64_i32 v[24:25], s[40:41], v11, s37, v[12:13]
	v_mad_i64_i32 v[26:27], s[40:41], v9, s37, v[12:13]
	v_mad_i64_i32 v[28:29], s[40:41], v19, s37, v[12:13]
	v_mad_i64_i32 v[30:31], s[40:41], v14, s37, v[12:13]
	v_mad_i64_i32 v[32:33], s[40:41], v32, s37, v[12:13]
	v_mad_i64_i32 v[34:35], s[40:41], v34, s37, v[12:13]
	v_mad_i64_i32 v[36:37], s[40:41], v36, s37, v[12:13]
	v_mad_i64_i32 v[38:39], s[40:41], v38, s37, v[12:13]
	v_mad_i64_i32 v[40:41], s[40:41], v40, s37, v[12:13]
	v_mad_i64_i32 v[42:43], s[40:41], v42, s37, v[12:13]
	v_mad_i64_i32 v[44:45], s[40:41], v44, s37, v[12:13]
	v_mad_i64_i32 v[46:47], s[40:41], v46, s37, v[12:13]
	v_mad_i64_i32 v[48:49], s[40:41], v48, s37, v[12:13]
	v_mad_i64_i32 v[50:51], s[40:41], v50, s37, v[12:13]
	global_load_dword v9, v[20:21], off nt
	global_load_dword v11, v[22:23], off nt
	global_load_dword v14, v[24:25], off nt
	global_load_dword v19, v[26:27], off nt
	global_load_dword v52, v[28:29], off nt
	global_load_dword v53, v[30:31], off nt
	global_load_dword v54, v[32:33], off nt
	global_load_dword v55, v[34:35], off nt
	global_load_dword v56, v[36:37], off nt
	global_load_dword v57, v[38:39], off nt
	global_load_dword v58, v[40:41], off nt
	global_load_dword v59, v[42:43], off nt
	global_load_dword v60, v[44:45], off nt
	global_load_dword v61, v[46:47], off nt
	global_load_dword v62, v[48:49], off nt
	global_load_dword v63, v[50:51], off nt
	v_or_b32_e32 v22, s42, v1
	v_or_b32_e32 v20, s43, v2
	s_add_i32 s27, s27, 16
	s_add_i32 s2, s2, 16
	s_add_i32 s29, s29, -16
	v_mad_u64_u32 v[20:21], s[40:41], v20, s35, v[6:7]
	v_mad_u64_u32 v[22:23], s[40:41], v22, s35, v[6:7]
	v_or_b32_e32 v21, s44, v1
	v_or_b32_e32 v23, s45, v2
	v_or_b32_e32 v30, s46, v1
	v_or_b32_e32 v28, s47, v2
	v_or_b32_e32 v34, s48, v1
	v_or_b32_e32 v32, s49, v2
	v_or_b32_e32 v38, s50, v1
	v_or_b32_e32 v36, s51, v2
	v_or_b32_e32 v42, s52, v1
	v_or_b32_e32 v40, s53, v2
	v_or_b32_e32 v46, s54, v1
	v_or_b32_e32 v44, s55, v2
	v_or_b32_e32 v50, s56, v1
	v_or_b32_e32 v48, s57, v2
	s_cmp_lg_u32 s29, 0
	v_mad_u64_u32 v[24:25], s[40:41], v23, s35, v[6:7]
	v_mad_u64_u32 v[26:27], s[40:41], v21, s35, v[6:7]
	v_mad_u64_u32 v[28:29], s[40:41], v28, s35, v[6:7]
	v_mad_u64_u32 v[30:31], s[40:41], v30, s35, v[6:7]
	v_mad_u64_u32 v[32:33], s[40:41], v32, s35, v[6:7]
	v_mad_u64_u32 v[34:35], s[40:41], v34, s35, v[6:7]
	v_mad_u64_u32 v[36:37], s[40:41], v36, s35, v[6:7]
	v_mad_u64_u32 v[38:39], s[40:41], v38, s35, v[6:7]
	v_mad_u64_u32 v[40:41], s[40:41], v40, s35, v[6:7]
	v_mad_u64_u32 v[42:43], s[40:41], v42, s35, v[6:7]
	v_mad_u64_u32 v[44:45], s[40:41], v44, s35, v[6:7]
	v_mad_u64_u32 v[46:47], s[40:41], v46, s35, v[6:7]
	v_mad_u64_u32 v[48:49], s[40:41], v48, s35, v[6:7]
	v_mad_u64_u32 v[50:51], s[40:41], v50, s35, v[6:7]
	s_waitcnt vmcnt(15)
	ds_write_b32 v20, v9
	s_waitcnt vmcnt(14)
	ds_write_b32 v22, v11
	s_waitcnt vmcnt(13)
	ds_write_b32 v24, v14
	s_waitcnt vmcnt(12)
	ds_write_b32 v26, v19
	s_waitcnt vmcnt(11)
	ds_write_b32 v28, v52
	s_waitcnt vmcnt(10)
	ds_write_b32 v30, v53
	s_waitcnt vmcnt(9)
	ds_write_b32 v32, v54
	s_waitcnt vmcnt(8)
	ds_write_b32 v34, v55
	s_waitcnt vmcnt(7)
	ds_write_b32 v36, v56
	s_waitcnt vmcnt(6)
	ds_write_b32 v38, v57
	s_waitcnt vmcnt(5)
	ds_write_b32 v40, v58
	s_waitcnt vmcnt(4)
	ds_write_b32 v42, v59
	s_waitcnt vmcnt(3)
	ds_write_b32 v44, v60
	s_waitcnt vmcnt(2)
	ds_write_b32 v46, v61
	s_waitcnt vmcnt(1)
	ds_write_b32 v48, v62
	s_waitcnt vmcnt(0)
	ds_write_b32 v50, v63
	s_cbranch_scc1 .LBB0_46
	s_waitcnt lgkmcnt(0)
	s_ashr_i32 s29, s28, 31
	ds_read2_b32 v[12:13], v15 offset0:33 offset1:41
	ds_read2_b32 v[24:25], v15 offset1:8
	ds_read2_b32 v[26:27], v15 offset0:66 offset1:74
	ds_read2_b32 v[28:29], v15 offset0:99 offset1:107
	ds_read2_b32 v[30:31], v15 offset0:132 offset1:140
	ds_read2_b32 v[32:33], v15 offset0:165 offset1:173
	ds_read2_b32 v[34:35], v15 offset0:198 offset1:206
	ds_read2_b32 v[36:37], v15 offset0:231 offset1:239
	s_lshl_b64 s[28:29], s[28:29], 1
	s_add_u32 s28, s38, s28
	v_or_b32_e32 v40, s26, v7
	s_addc_u32 s29, s39, s29
	v_mov_b32_e32 v11, v5
	v_ashrrev_i32_e32 v41, 31, v40
	v_lshl_add_u64 v[38:39], s[28:29], 0, v[10:11]
	v_lshlrev_b64 v[40:41], 11, v[40:41]
	s_waitcnt lgkmcnt(6)
	v_cvt_pk_bf16_f32 v20, v24, v12
	s_waitcnt lgkmcnt(4)
	v_cvt_pk_bf16_f32 v21, v26, v28
	s_waitcnt lgkmcnt(2)
	v_cvt_pk_bf16_f32 v22, v30, v32
	s_waitcnt lgkmcnt(0)
	v_cvt_pk_bf16_f32 v23, v34, v36
	v_lshl_add_u64 v[40:41], v[38:39], 0, v[40:41]
	v_or_b32_e32 v12, s26, v16
	global_store_dwordx4 v[40:41], v[20:23], off
	s_nop 1
	v_cvt_pk_bf16_f32 v20, v25, v13
	v_ashrrev_i32_e32 v13, 31, v12
	v_cvt_pk_bf16_f32 v21, v27, v29
	v_cvt_pk_bf16_f32 v22, v31, v33
	v_cvt_pk_bf16_f32 v23, v35, v37
	v_lshlrev_b64 v[12:13], 11, v[12:13]
	ds_read2_b32 v[24:25], v15 offset0:49 offset1:57
	ds_read2_b32 v[26:27], v15 offset0:16 offset1:24
	ds_read2_b32 v[28:29], v15 offset0:82 offset1:90
	ds_read2_b32 v[30:31], v15 offset0:115 offset1:123
	ds_read2_b32 v[32:33], v15 offset0:148 offset1:156
	ds_read2_b32 v[34:35], v15 offset0:181 offset1:189
	ds_read2_b32 v[36:37], v15 offset0:214 offset1:222
	ds_read2_b32 v[40:41], v15 offset0:247 offset1:255
	v_lshl_add_u64 v[12:13], v[38:39], 0, v[12:13]
	global_store_dwordx4 v[12:13], v[20:23], off
	v_or_b32_e32 v12, s26, v17
	v_ashrrev_i32_e32 v13, 31, v12
	v_lshlrev_b64 v[12:13], 11, v[12:13]
	s_waitcnt lgkmcnt(6)
	v_cvt_pk_bf16_f32 v20, v26, v24
	s_waitcnt lgkmcnt(4)
	v_cvt_pk_bf16_f32 v21, v28, v30
	s_waitcnt lgkmcnt(2)
	v_cvt_pk_bf16_f32 v22, v32, v34
	s_waitcnt lgkmcnt(0)
	v_cvt_pk_bf16_f32 v23, v36, v40
	v_lshl_add_u64 v[12:13], v[38:39], 0, v[12:13]
	global_store_dwordx4 v[12:13], v[20:23], off
	v_or_b32_e32 v12, s26, v18
	v_ashrrev_i32_e32 v13, 31, v12
	v_lshlrev_b64 v[12:13], 11, v[12:13]
	v_cvt_pk_bf16_f32 v20, v27, v25
	v_cvt_pk_bf16_f32 v21, v29, v31
	v_cvt_pk_bf16_f32 v22, v33, v35
	v_cvt_pk_bf16_f32 v23, v37, v41
	v_lshl_add_u64 v[12:13], v[38:39], 0, v[12:13]
	global_store_dwordx4 v[12:13], v[20:23], off
	s_waitcnt lgkmcnt(0)
	s_branch .LBB0_15

; __device__ __forceinline__ unsigned pk2(float lo, float hi) { return pg8::cvt_pk_bf16(lo, hi); }
; __device__ __forceinline__ void cvt_panel(int pm, const float* x, bf16* xb) {
;     ...
; #pragma unroll 4
;     for (int i = tid; i < 256 * DM / 8; i += NTHR) { const f32x4 a = *(const f32x4*)(src + (size_t)i * 8), b = *(const f32x4*)(src + (size_t)i * 8 + 4);
;         u32x4 w; w.x = pk2(a.x, a.y); w.y = pk2(a.z, a.w); w.z = pk2(b.x, b.y); w.w = pk2(b.z, b.w); *(u32x4*)(dst + (size_t)i * 8) = w; }
.LBB0_54:
	v_lshl_add_u64 v[12:13], s[10:11], 0, v[4:5]
	global_load_dwordx4 v[8:11], v[12:13], off nt
	global_load_dwordx4 v[16:19], v[12:13], off offset:16 nt
	v_add_co_u32_e32 v6, vcc, 1, v6
	v_add_u32_e32 v14, 0x200, v14
	v_lshl_add_u64 v[4:5], v[4:5], 0, s[16:17]
	s_or_b64 s[24:25], vcc, s[24:25]
	s_waitcnt vmcnt(1)
	v_cvt_pk_bf16_f32 v8, v8, v9
	v_cvt_pk_bf16_f32 v9, v10, v11
	s_waitcnt vmcnt(0)
	v_cvt_pk_bf16_f32 v10, v16, v17
	v_cvt_pk_bf16_f32 v11, v18, v19
	global_store_dwordx4 v[2:3], v[8:11], off
	v_lshl_add_u64 v[2:3], v[2:3], 0, s[14:15]
	s_andn2_b64 exec, exec, s[24:25]
	s_cbranch_execnz .LBB0_54
	s_or_b64 exec, exec, s[24:25]

; __device__ __forceinline__ unsigned pk2(float lo, float hi) { return pg8::cvt_pk_bf16(lo, hi); }
; __device__ __forceinline__ void cvt_panel(int pm, const float* x, bf16* xb) {
;     ...
; #pragma unroll 4
;     for (int i = tid; i < 256 * DM / 8; i += NTHR) { const f32x4 a = *(const f32x4*)(src + (size_t)i * 8), b = *(const f32x4*)(src + (size_t)i * 8 + 4);
;         u32x4 w; w.x = pk2(a.x, a.y); w.y = pk2(a.z, a.w); w.z = pk2(b.x, b.y); w.w = pk2(b.z, b.w); *(u32x4*)(dst + (size_t)i * 8) = w; }
.LBB0_58:
	global_load_dwordx4 v[28:31], v[10:11], off nt
	global_load_dwordx4 v[32:35], v[10:11], off offset:16 nt
	global_load_dwordx4 v[36:39], v[16:17], off nt
	global_load_dwordx4 v[40:43], v[16:17], off offset:16 nt
	global_load_dwordx4 v[44:47], v[12:13], off nt
	global_load_dwordx4 v[48:51], v[12:13], off offset:16 nt
	global_load_dwordx4 v[52:55], v[6:7], off nt
	global_load_dwordx4 v[56:59], v[6:7], off offset:16 nt
	v_lshl_add_u64 v[18:19], s[24:25], 0, v[4:5]
	v_lshl_add_u64 v[20:21], s[24:25], 0, v[14:15]
	v_lshl_add_u64 v[22:23], s[24:25], 0, v[8:9]
	v_lshl_add_u64 v[24:25], s[24:25], 0, v[2:3]
	v_add_u32_e32 v1, 0x800, v1
	v_cmp_lt_i32_e32 vcc, s29, v1
	v_lshl_add_u64 v[10:11], v[10:11], 0, s[18:19]
	v_lshl_add_u64 v[16:17], v[16:17], 0, s[18:19]
	v_lshl_add_u64 v[12:13], v[12:13], 0, s[18:19]
	v_lshl_add_u64 v[6:7], v[6:7], 0, s[18:19]
	s_add_u32 s24, s24, 0x8000
	s_addc_u32 s25, s25, 0
	s_or_b64 s[22:23], vcc, s[22:23]
	s_waitcnt vmcnt(6)
	v_cvt_pk_bf16_f32 v28, v28, v29
	v_cvt_pk_bf16_f32 v29, v30, v31
	v_cvt_pk_bf16_f32 v30, v32, v33
	v_cvt_pk_bf16_f32 v31, v34, v35
	global_store_dwordx4 v[18:19], v[28:31], off
	s_waitcnt vmcnt(5)
	v_cvt_pk_bf16_f32 v36, v36, v37
	v_cvt_pk_bf16_f32 v37, v38, v39
	v_cvt_pk_bf16_f32 v38, v40, v41
	v_cvt_pk_bf16_f32 v39, v42, v43
	global_store_dwordx4 v[20:21], v[36:39], off
	s_waitcnt vmcnt(4)
	v_cvt_pk_bf16_f32 v44, v44, v45
	v_cvt_pk_bf16_f32 v45, v46, v47
	v_cvt_pk_bf16_f32 v46, v48, v49
	v_cvt_pk_bf16_f32 v47, v50, v51
	global_store_dwordx4 v[22:23], v[44:47], off
	s_waitcnt vmcnt(3)
	v_cvt_pk_bf16_f32 v52, v52, v53
	v_cvt_pk_bf16_f32 v53, v54, v55
	v_cvt_pk_bf16_f32 v54, v56, v57
	v_cvt_pk_bf16_f32 v55, v58, v59
	global_store_dwordx4 v[24:25], v[52:55], off
	s_andn2_b64 exec, exec, s[22:23]
	s_cbranch_execnz .LBB0_58
	s_branch .LBB0_50
